# v56 with the missing wait state restored between an M0 write and its LDS-DMA load (hazard-clean saddr K-loop)
# speedup vs baseline: 1.0168x; 1.0012x over previous
; #define PG8_STAGE(bufoff, gbase, voff) do { _Pragma("unroll") for (int _i = 0; _i < 2; ++_i) \
;         __builtin_amdgcn_global_load_lds((const unsigned*)((const char*)(gbase) + (voff)[_i]), (LAS unsigned*)(lds + (bufoff) + ldsw + _i * 8192), 16, 0, 0); } while (0)
; #define PG8_LDA(dst, b, h) do { _Pragma("unroll") for (int m = 0; m < 4; ++m) _Pragma("unroll") for (int k = 0; k < 2; ++k) dst[m][k] = *(const LAS bf16x8*)(lds + PG8_SA(b, h) + aoff + m * 2048 + k * 1024); } while (0)
; #define PG8_LDB(dst, b, h) do { _Pragma("unroll") for (int n = 0; n < 2; ++n) _Pragma("unroll") for (int k = 0; k < 2; ++k) dst[n][k] = *(const LAS bf16x8*)(lds + PG8_SB(b, h) + boff + n * 2048 + k * 1024); } while (0)
; #define PG8_MMA(ai, bj, At, Bt) do { __builtin_amdgcn_s_setprio(1); _Pragma("unroll") for (int m = 0; m < 4; ++m) _Pragma("unroll") for (int n = 0; n < 2; ++n) _Pragma("unroll") for (int k = 0; k < 2; ++k) \
;         acc[ai][bj][m][n] = __builtin_amdgcn_mfma_f32_16x16x32_bf16(Bt[n][k], At[m][k], acc[ai][bj][m][n], 0, 0, 0); __builtin_amdgcn_s_setprio(0); } while (0)
; #define PG8_WAIT_V(n) asm volatile("s_waitcnt vmcnt(" #n ")" ::: "memory")
; #define PG8_WAIT_L(n) asm volatile("s_waitcnt lgkmcnt(" #n ")" ::: "memory")
; #define PG8_BAR __builtin_amdgcn_s_barrier()
; template <class Epi>
; __device__ __forceinline__ void gemm_phase(LAS unsigned char* lds, const Gemm g, const StaticOrder& S, const Epi& E) {
;     ...
;         for (; t < tend; t += 2) {
;             const bool last = (t == nt - 2);
;             const char* a1 = cA + (size_t)(t + 1) * kstep;
;             const char* a2 = last ? nA : cA + (size_t)(t + 2) * kstep; const char* b2 = last ? nB : cB + (size_t)(t + 2) * kstep;
;             const char* a3 = a2 + kstep; const char* b3 = b2 + kstep;
;             PG8_LDB(B0, 0, 0); PG8_SCHED; PG8_LDA(At, 0, 0); PG8_STAGE(PG8_SA(1, 1), a1 + hstep, voffA);
;             PG8_WAIT_L(8); PG8_BAR; PG8_WAIT_L(0); PG8_MMA(0, 0, At, B0); PG8_BAR; PG8_SCHED;
;             PG8_LDB(B1, 0, 1); PG8_STAGE(PG8_SB(0, 0), b2, voffB);
;             PG8_BAR; PG8_WAIT_L(0); PG8_MMA(0, 1, At, B1); PG8_BAR;
;             PG8_LDA(At, 0, 1); PG8_STAGE(PG8_SA(0, 0), a2, voffA);
;             PG8_BAR; PG8_WAIT_L(0); PG8_MMA(1, 0, At, B0); PG8_BAR; PG8_SCHED;
;             PG8_STAGE(PG8_SB(0, 1), b2 + hstep, voffB);
;             PG8_WAIT_V(6); PG8_BAR; PG8_MMA(1, 1, At, B1); PG8_BAR;
.LBB0_206:
	s_add_i32 s78, 0, 0x10000
	ds_read_b128 v[132:135], v234
	ds_read_b128 v[136:139], v234 offset:1024
	ds_read_b128 v[140:143], v234 offset:2048
	ds_read_b128 v[144:147], v234 offset:3072
	s_add_i32 s76, s2, 1
	s_mov_b32 s47, s2
	s_add_i32 s2, s2, 2
	s_ashr_i32 s77, s76, 31
	s_cmp_eq_u32 s67, s47
	s_cselect_b32 s75, s43, s46
	s_cselect_b32 s74, s42, vcc_hi
	s_cselect_b32 s93, s63, vcc_lo
	s_cselect_b32 s92, s62, s3
	s_lshl_b64 s[76:77], s[76:77], 7
	s_add_u32 s76, s5, s76
	s_addc_u32 s77, s31, s77
	s_add_i32 m0, s11, 0xc000
	ds_read_b128 v[148:151], v200
	ds_read_b128 v[152:155], v200 offset:1024
	ds_read_b128 v[156:159], v200 offset:2048
	ds_read_b128 v[160:163], v200 offset:3072
	ds_read_b128 v[164:167], v200 offset:4096
	ds_read_b128 v[186:189], v200 offset:5120
	ds_read_b128 v[190:193], v200 offset:6144
	ds_read_b128 v[202:205], v200 offset:7168
	global_load_lds_dwordx4 v168, s[76:77]
	s_add_i32 m0, s11, 0xe000
	s_nop 0
	global_load_lds_dwordx4 v172, s[76:77]
	s_waitcnt lgkmcnt(0)
	s_barrier
	v_mfma_f32_16x16x32_bf16 v[128:131], v[132:135], v[148:151], v[128:131]
	v_mfma_f32_16x16x32_bf16 v[124:127], v[140:143], v[148:151], v[124:127]
	v_mfma_f32_16x16x32_bf16 v[112:115], v[132:135], v[156:159], v[112:115]
	v_mfma_f32_16x16x32_bf16 v[108:111], v[140:143], v[156:159], v[108:111]
	v_mfma_f32_16x16x32_bf16 v[96:99], v[132:135], v[164:167], v[96:99]
	v_mfma_f32_16x16x32_bf16 v[92:95], v[140:143], v[164:167], v[92:95]
	v_mfma_f32_16x16x32_bf16 v[80:83], v[132:135], v[190:193], v[80:83]
	v_mfma_f32_16x16x32_bf16 v[76:79], v[140:143], v[190:193], v[76:79]
	v_mfma_f32_16x16x32_bf16 v[128:131], v[136:139], v[152:155], v[128:131]
	v_mfma_f32_16x16x32_bf16 v[124:127], v[144:147], v[152:155], v[124:127]
	v_mfma_f32_16x16x32_bf16 v[112:115], v[136:139], v[160:163], v[112:115]
	v_mfma_f32_16x16x32_bf16 v[108:111], v[144:147], v[160:163], v[108:111]
	v_mfma_f32_16x16x32_bf16 v[96:99], v[136:139], v[186:189], v[96:99]
	v_mfma_f32_16x16x32_bf16 v[92:95], v[144:147], v[186:189], v[92:95]
	v_mfma_f32_16x16x32_bf16 v[80:83], v[136:139], v[202:205], v[80:83]
	v_mfma_f32_16x16x32_bf16 v[76:79], v[144:147], v[202:205], v[76:79]
	s_barrier
	s_add_i32 s47, 0, 0x14000
	s_add_i32 s76, s78, s6
	s_mov_b32 m0, s76
	ds_read_b128 v[206:209], v235
	ds_read_b128 v[222:225], v235 offset:1024
	ds_read_b128 v[226:229], v235 offset:2048
	ds_read_b128 v[230:233], v235 offset:3072
	global_load_lds_dwordx4 v170, s[92:93]
	s_add_i32 m0, s76, 0x2000
	s_nop 0
	global_load_lds_dwordx4 v174, s[92:93]
	s_waitcnt lgkmcnt(0)
	s_barrier
	v_mfma_f32_16x16x32_bf16 v[120:123], v[206:209], v[148:151], v[120:123]
	v_mfma_f32_16x16x32_bf16 v[116:119], v[226:229], v[148:151], v[116:119]
	v_mfma_f32_16x16x32_bf16 v[104:107], v[206:209], v[156:159], v[104:107]
	v_mfma_f32_16x16x32_bf16 v[100:103], v[226:229], v[156:159], v[100:103]
	v_mfma_f32_16x16x32_bf16 v[88:91], v[206:209], v[164:167], v[88:91]
	v_mfma_f32_16x16x32_bf16 v[84:87], v[226:229], v[164:167], v[84:87]
	v_mfma_f32_16x16x32_bf16 v[72:75], v[206:209], v[190:193], v[72:75]
	v_mfma_f32_16x16x32_bf16 v[68:71], v[226:229], v[190:193], v[68:71]
	v_mfma_f32_16x16x32_bf16 v[120:123], v[222:225], v[152:155], v[120:123]
	v_mfma_f32_16x16x32_bf16 v[116:119], v[230:233], v[152:155], v[116:119]
	v_mfma_f32_16x16x32_bf16 v[104:107], v[222:225], v[160:163], v[104:107]
	v_mfma_f32_16x16x32_bf16 v[100:103], v[230:233], v[160:163], v[100:103]
	v_mfma_f32_16x16x32_bf16 v[88:91], v[222:225], v[186:189], v[88:91]
	v_mfma_f32_16x16x32_bf16 v[84:87], v[230:233], v[186:189], v[84:87]
	v_mfma_f32_16x16x32_bf16 v[72:75], v[222:225], v[202:205], v[72:75]
	v_mfma_f32_16x16x32_bf16 v[68:71], v[230:233], v[202:205], v[68:71]
	s_mov_b32 m0, s11
	s_barrier
	ds_read_b128 v[148:151], v200 offset:16384
	ds_read_b128 v[152:155], v200 offset:17408
	ds_read_b128 v[156:159], v200 offset:18432
	ds_read_b128 v[160:163], v200 offset:19456
	ds_read_b128 v[164:167], v200 offset:20480
	ds_read_b128 v[186:189], v200 offset:21504
	ds_read_b128 v[190:193], v200 offset:22528
	ds_read_b128 v[202:205], v200 offset:23552
	global_load_lds_dwordx4 v168, s[74:75]
	s_mov_b32 m0, s70
	s_nop 0
	global_load_lds_dwordx4 v172, s[74:75]
	s_waitcnt lgkmcnt(0)
	s_barrier
	v_mfma_f32_16x16x32_bf16 v[64:67], v[132:135], v[148:151], v[64:67]
	v_mfma_f32_16x16x32_bf16 v[60:63], v[140:143], v[148:151], v[60:63]
	v_mfma_f32_16x16x32_bf16 v[48:51], v[132:135], v[156:159], v[48:51]
	v_mfma_f32_16x16x32_bf16 v[44:47], v[140:143], v[156:159], v[44:47]
	v_mfma_f32_16x16x32_bf16 v[32:35], v[132:135], v[164:167], v[32:35]
	v_mfma_f32_16x16x32_bf16 v[28:31], v[140:143], v[164:167], v[28:31]
	v_mfma_f32_16x16x32_bf16 v[16:19], v[132:135], v[190:193], v[16:19]
	v_mfma_f32_16x16x32_bf16 v[12:15], v[140:143], v[190:193], v[12:15]
	v_mfma_f32_16x16x32_bf16 v[64:67], v[136:139], v[152:155], v[64:67]
	v_mfma_f32_16x16x32_bf16 v[60:63], v[144:147], v[152:155], v[60:63]
	v_mfma_f32_16x16x32_bf16 v[48:51], v[136:139], v[160:163], v[48:51]
	v_mfma_f32_16x16x32_bf16 v[44:47], v[144:147], v[160:163], v[44:47]
	v_mfma_f32_16x16x32_bf16 v[32:35], v[136:139], v[186:189], v[32:35]
	v_mfma_f32_16x16x32_bf16 v[28:31], v[144:147], v[186:189], v[28:31]
	v_mfma_f32_16x16x32_bf16 v[16:19], v[136:139], v[202:205], v[16:19]
	v_mfma_f32_16x16x32_bf16 v[12:15], v[144:147], v[202:205], v[12:15]
	s_barrier
	s_add_u32 s76, s92, s13
	s_addc_u32 s77, s93, 0
	s_add_i32 s47, s47, s6
	s_mov_b32 m0, s47
	s_nop 0
	global_load_lds_dwordx4 v170, s[76:77]
	s_add_i32 m0, s47, 0x2000
	s_nop 0
	global_load_lds_dwordx4 v174, s[76:77]
	s_waitcnt vmcnt(6)
	s_barrier
; #define PG8_STAGE(bufoff, gbase, voff) do { _Pragma("unroll") for (int _i = 0; _i < 2; ++_i) \
;         __builtin_amdgcn_global_load_lds((const unsigned*)((const char*)(gbase) + (voff)[_i]), (LAS unsigned*)(lds + (bufoff) + ldsw + _i * 8192), 16, 0, 0); } while (0)
; #define PG8_LDA(dst, b, h) do { _Pragma("unroll") for (int m = 0; m < 4; ++m) _Pragma("unroll") for (int k = 0; k < 2; ++k) dst[m][k] = *(const LAS bf16x8*)(lds + PG8_SA(b, h) + aoff + m * 2048 + k * 1024); } while (0)
; #define PG8_LDB(dst, b, h) do { _Pragma("unroll") for (int n = 0; n < 2; ++n) _Pragma("unroll") for (int k = 0; k < 2; ++k) dst[n][k] = *(const LAS bf16x8*)(lds + PG8_SB(b, h) + boff + n * 2048 + k * 1024); } while (0)
; #define PG8_MMA(ai, bj, At, Bt) do { __builtin_amdgcn_s_setprio(1); _Pragma("unroll") for (int m = 0; m < 4; ++m) _Pragma("unroll") for (int n = 0; n < 2; ++n) _Pragma("unroll") for (int k = 0; k < 2; ++k) \
;         acc[ai][bj][m][n] = __builtin_amdgcn_mfma_f32_16x16x32_bf16(Bt[n][k], At[m][k], acc[ai][bj][m][n], 0, 0, 0); __builtin_amdgcn_s_setprio(0); } while (0)
; #define PG8_WAIT_V(n) asm volatile("s_waitcnt vmcnt(" #n ")" ::: "memory")
; #define PG8_WAIT_L(n) asm volatile("s_waitcnt lgkmcnt(" #n ")" ::: "memory")
; #define PG8_BAR __builtin_amdgcn_s_barrier()
; #define PG8_SCHED __builtin_amdgcn_sched_barrier(0)
; template <class Epi>
; __device__ __forceinline__ void gemm_phase(LAS unsigned char* lds, const Gemm g, const StaticOrder& S, const Epi& E) {
;     ...
;             PG8_WAIT_V(6); PG8_BAR; PG8_MMA(1, 1, At, B1); PG8_BAR;
;             PG8_LDB(B0, 1, 0); PG8_SCHED; PG8_LDA(At, 1, 0); PG8_STAGE(PG8_SA(0, 1), a2 + hstep, voffA);
;             PG8_WAIT_L(8); PG8_BAR; PG8_WAIT_L(0); PG8_MMA(0, 0, At, B0); PG8_BAR; PG8_SCHED;
;             PG8_LDB(B1, 1, 1); PG8_STAGE(PG8_SB(1, 0), b3, voffB);
;             PG8_BAR; PG8_WAIT_L(0); PG8_MMA(0, 1, At, B1); PG8_BAR;
;             PG8_LDA(At, 1, 1); PG8_STAGE(PG8_SA(1, 0), a3, voffA);
;             PG8_BAR; PG8_WAIT_L(0); PG8_MMA(1, 0, At, B0); PG8_BAR; PG8_SCHED;
	v_mfma_f32_16x16x32_bf16 v[56:59], v[206:209], v[148:151], v[56:59]
	v_mfma_f32_16x16x32_bf16 v[52:55], v[226:229], v[148:151], v[52:55]
	v_mfma_f32_16x16x32_bf16 v[40:43], v[206:209], v[156:159], v[40:43]
	v_mfma_f32_16x16x32_bf16 v[36:39], v[226:229], v[156:159], v[36:39]
	v_mfma_f32_16x16x32_bf16 v[24:27], v[206:209], v[164:167], v[24:27]
	v_mfma_f32_16x16x32_bf16 v[20:23], v[226:229], v[164:167], v[20:23]
	v_mfma_f32_16x16x32_bf16 v[8:11], v[206:209], v[190:193], v[8:11]
	v_mfma_f32_16x16x32_bf16 v[4:7], v[226:229], v[190:193], v[4:7]
	v_mfma_f32_16x16x32_bf16 v[56:59], v[222:225], v[152:155], v[56:59]
	v_mfma_f32_16x16x32_bf16 v[52:55], v[230:233], v[152:155], v[52:55]
	v_mfma_f32_16x16x32_bf16 v[40:43], v[222:225], v[160:163], v[40:43]
	v_mfma_f32_16x16x32_bf16 v[36:39], v[230:233], v[160:163], v[36:39]
	v_mfma_f32_16x16x32_bf16 v[24:27], v[222:225], v[186:189], v[24:27]
	v_mfma_f32_16x16x32_bf16 v[20:23], v[230:233], v[186:189], v[20:23]
	v_mfma_f32_16x16x32_bf16 v[8:11], v[222:225], v[202:205], v[8:11]
	v_mfma_f32_16x16x32_bf16 v[4:7], v[230:233], v[202:205], v[4:7]
	s_add_i32 s47, 0, 0x18000
	s_barrier
	ds_read_b128 v[132:135], v236
	ds_read_b128 v[136:139], v236 offset:1024
	ds_read_b128 v[140:143], v236 offset:2048
	ds_read_b128 v[144:147], v236 offset:3072
	s_add_u32 s76, s74, s13
	s_addc_u32 s77, s75, 0
	s_mov_b32 m0, s71
	ds_read_b128 v[148:151], v200 offset:32768
	ds_read_b128 v[152:155], v200 offset:33792
	ds_read_b128 v[156:159], v200 offset:34816
	ds_read_b128 v[160:163], v200 offset:35840
	ds_read_b128 v[164:167], v200 offset:36864
	ds_read_b128 v[186:189], v200 offset:37888
	ds_read_b128 v[190:193], v200 offset:38912
	ds_read_b128 v[202:205], v200 offset:39936
	global_load_lds_dwordx4 v168, s[76:77]
	s_mov_b32 m0, s19
	s_nop 0
	global_load_lds_dwordx4 v172, s[76:77]
	s_waitcnt lgkmcnt(0)
	s_barrier
	v_mfma_f32_16x16x32_bf16 v[128:131], v[132:135], v[148:151], v[128:131]
	v_mfma_f32_16x16x32_bf16 v[124:127], v[140:143], v[148:151], v[124:127]
	v_mfma_f32_16x16x32_bf16 v[112:115], v[132:135], v[156:159], v[112:115]
	v_mfma_f32_16x16x32_bf16 v[108:111], v[140:143], v[156:159], v[108:111]
	v_mfma_f32_16x16x32_bf16 v[96:99], v[132:135], v[164:167], v[96:99]
	v_mfma_f32_16x16x32_bf16 v[92:95], v[140:143], v[164:167], v[92:95]
	v_mfma_f32_16x16x32_bf16 v[80:83], v[132:135], v[190:193], v[80:83]
	v_mfma_f32_16x16x32_bf16 v[76:79], v[140:143], v[190:193], v[76:79]
	v_mfma_f32_16x16x32_bf16 v[128:131], v[136:139], v[152:155], v[128:131]
	v_mfma_f32_16x16x32_bf16 v[124:127], v[144:147], v[152:155], v[124:127]
	v_mfma_f32_16x16x32_bf16 v[112:115], v[136:139], v[160:163], v[112:115]
	v_mfma_f32_16x16x32_bf16 v[108:111], v[144:147], v[160:163], v[108:111]
	v_mfma_f32_16x16x32_bf16 v[96:99], v[136:139], v[186:189], v[96:99]
	v_mfma_f32_16x16x32_bf16 v[92:95], v[144:147], v[186:189], v[92:95]
	v_mfma_f32_16x16x32_bf16 v[80:83], v[136:139], v[202:205], v[80:83]
	v_mfma_f32_16x16x32_bf16 v[76:79], v[144:147], v[202:205], v[76:79]
	s_barrier
	s_add_i32 s47, s47, s6
	s_add_u32 s76, s92, 0x80
	s_addc_u32 s77, s93, 0
	s_mov_b32 m0, s47
	ds_read_b128 v[206:209], v237
	ds_read_b128 v[222:225], v237 offset:1024
	ds_read_b128 v[226:229], v237 offset:2048
	ds_read_b128 v[230:233], v237 offset:3072
	global_load_lds_dwordx4 v170, s[76:77]
	s_add_i32 m0, s47, 0x2000
	s_nop 0
	global_load_lds_dwordx4 v174, s[76:77]
	s_waitcnt lgkmcnt(0)
	s_barrier
; #define PG8_STAGE(bufoff, gbase, voff) do { _Pragma("unroll") for (int _i = 0; _i < 2; ++_i) \
;         __builtin_amdgcn_global_load_lds((const unsigned*)((const char*)(gbase) + (voff)[_i]), (LAS unsigned*)(lds + (bufoff) + ldsw + _i * 8192), 16, 0, 0); } while (0)
; #define PG8_MMA(ai, bj, At, Bt) do { __builtin_amdgcn_s_setprio(1); _Pragma("unroll") for (int m = 0; m < 4; ++m) _Pragma("unroll") for (int n = 0; n < 2; ++n) _Pragma("unroll") for (int k = 0; k < 2; ++k) \
;         acc[ai][bj][m][n] = __builtin_amdgcn_mfma_f32_16x16x32_bf16(Bt[n][k], At[m][k], acc[ai][bj][m][n], 0, 0, 0); __builtin_amdgcn_s_setprio(0); } while (0)
; #define PG8_WAIT_V(n) asm volatile("s_waitcnt vmcnt(" #n ")" ::: "memory")
; #define PG8_WAIT_L(n) asm volatile("s_waitcnt lgkmcnt(" #n ")" ::: "memory")
; #define PG8_BAR __builtin_amdgcn_s_barrier()
; #define PG8_SCHED __builtin_amdgcn_sched_barrier(0)
; template <class Epi>
; __device__ __forceinline__ void gemm_phase(LAS unsigned char* lds, const Gemm g, const StaticOrder& S, const Epi& E) {
;     ...
;             PG8_BAR; PG8_WAIT_L(0); PG8_MMA(1, 0, At, B0); PG8_BAR; PG8_SCHED;
;             PG8_STAGE(PG8_SB(1, 1), b3 + hstep, voffB);
;             PG8_WAIT_V(6); PG8_BAR; PG8_MMA(1, 1, At, B1); PG8_BAR;
	v_mfma_f32_16x16x32_bf16 v[120:123], v[206:209], v[148:151], v[120:123]
	v_mfma_f32_16x16x32_bf16 v[116:119], v[226:229], v[148:151], v[116:119]
	v_mfma_f32_16x16x32_bf16 v[104:107], v[206:209], v[156:159], v[104:107]
	v_mfma_f32_16x16x32_bf16 v[100:103], v[226:229], v[156:159], v[100:103]
	v_mfma_f32_16x16x32_bf16 v[88:91], v[206:209], v[164:167], v[88:91]
	v_mfma_f32_16x16x32_bf16 v[84:87], v[226:229], v[164:167], v[84:87]
	v_mfma_f32_16x16x32_bf16 v[72:75], v[206:209], v[190:193], v[72:75]
	v_mfma_f32_16x16x32_bf16 v[68:71], v[226:229], v[190:193], v[68:71]
	v_mfma_f32_16x16x32_bf16 v[120:123], v[222:225], v[152:155], v[120:123]
	v_mfma_f32_16x16x32_bf16 v[116:119], v[230:233], v[152:155], v[116:119]
	v_mfma_f32_16x16x32_bf16 v[104:107], v[222:225], v[160:163], v[104:107]
	v_mfma_f32_16x16x32_bf16 v[100:103], v[230:233], v[160:163], v[100:103]
	v_mfma_f32_16x16x32_bf16 v[88:91], v[222:225], v[186:189], v[88:91]
	v_mfma_f32_16x16x32_bf16 v[84:87], v[230:233], v[186:189], v[84:87]
	v_mfma_f32_16x16x32_bf16 v[72:75], v[222:225], v[202:205], v[72:75]
	v_mfma_f32_16x16x32_bf16 v[68:71], v[230:233], v[202:205], v[68:71]
	s_mov_b32 m0, s33
	s_add_u32 s76, s74, 0x80
	s_addc_u32 s77, s75, 0
	s_barrier
	ds_read_b128 v[148:151], v200 offset:49152
	ds_read_b128 v[152:155], v200 offset:50176
	ds_read_b128 v[156:159], v200 offset:51200
	ds_read_b128 v[160:163], v200 offset:52224
	ds_read_b128 v[164:167], v200 offset:53248
	ds_read_b128 v[186:189], v200 offset:54272
	ds_read_b128 v[190:193], v200 offset:55296
	ds_read_b128 v[202:205], v200 offset:56320
	global_load_lds_dwordx4 v168, s[76:77]
	s_mov_b32 m0, s66
	s_nop 0
	global_load_lds_dwordx4 v172, s[76:77]
	s_waitcnt lgkmcnt(0)
	s_barrier
	v_mfma_f32_16x16x32_bf16 v[64:67], v[132:135], v[148:151], v[64:67]
	v_mfma_f32_16x16x32_bf16 v[60:63], v[140:143], v[148:151], v[60:63]
	v_mfma_f32_16x16x32_bf16 v[48:51], v[132:135], v[156:159], v[48:51]
	v_mfma_f32_16x16x32_bf16 v[44:47], v[140:143], v[156:159], v[44:47]
	v_mfma_f32_16x16x32_bf16 v[32:35], v[132:135], v[164:167], v[32:35]
	v_mfma_f32_16x16x32_bf16 v[28:31], v[140:143], v[164:167], v[28:31]
	v_mfma_f32_16x16x32_bf16 v[16:19], v[132:135], v[190:193], v[16:19]
	v_mfma_f32_16x16x32_bf16 v[12:15], v[140:143], v[190:193], v[12:15]
	v_mfma_f32_16x16x32_bf16 v[64:67], v[136:139], v[152:155], v[64:67]
	v_mfma_f32_16x16x32_bf16 v[60:63], v[144:147], v[152:155], v[60:63]
	v_mfma_f32_16x16x32_bf16 v[48:51], v[136:139], v[160:163], v[48:51]
	v_mfma_f32_16x16x32_bf16 v[44:47], v[144:147], v[160:163], v[44:47]
	v_mfma_f32_16x16x32_bf16 v[32:35], v[136:139], v[186:189], v[32:35]
	v_mfma_f32_16x16x32_bf16 v[28:31], v[144:147], v[186:189], v[28:31]
	v_mfma_f32_16x16x32_bf16 v[16:19], v[136:139], v[202:205], v[16:19]
	v_mfma_f32_16x16x32_bf16 v[12:15], v[144:147], v[202:205], v[12:15]
	s_barrier
	s_add_i32 s47, s6, 0x1c000
	s_add_u32 s76, s92, s13
	s_addc_u32 s77, s93, 0
	s_add_u32 s76, s76, 0x80
	s_addc_u32 s77, s77, 0
	s_mov_b32 m0, s47
	s_nop 0
	global_load_lds_dwordx4 v170, s[76:77]
	s_add_i32 m0, s47, 0x2000
	s_nop 0
	global_load_lds_dwordx4 v174, s[76:77]
	s_waitcnt vmcnt(6)
	s_barrier
	v_mfma_f32_16x16x32_bf16 v[56:59], v[206:209], v[148:151], v[56:59]
	v_mfma_f32_16x16x32_bf16 v[52:55], v[226:229], v[148:151], v[52:55]
	v_mfma_f32_16x16x32_bf16 v[40:43], v[206:209], v[156:159], v[40:43]
	v_mfma_f32_16x16x32_bf16 v[36:39], v[226:229], v[156:159], v[36:39]
	v_mfma_f32_16x16x32_bf16 v[24:27], v[206:209], v[164:167], v[24:27]
	v_mfma_f32_16x16x32_bf16 v[20:23], v[226:229], v[164:167], v[20:23]
	v_mfma_f32_16x16x32_bf16 v[8:11], v[206:209], v[190:193], v[8:11]
	v_mfma_f32_16x16x32_bf16 v[4:7], v[226:229], v[190:193], v[4:7]
	v_mfma_f32_16x16x32_bf16 v[56:59], v[222:225], v[152:155], v[56:59]
	v_mfma_f32_16x16x32_bf16 v[52:55], v[230:233], v[152:155], v[52:55]
	v_mfma_f32_16x16x32_bf16 v[40:43], v[222:225], v[160:163], v[40:43]
	v_mfma_f32_16x16x32_bf16 v[36:39], v[230:233], v[160:163], v[36:39]
	v_mfma_f32_16x16x32_bf16 v[24:27], v[222:225], v[186:189], v[24:27]
	v_mfma_f32_16x16x32_bf16 v[20:23], v[230:233], v[186:189], v[20:23]
	v_mfma_f32_16x16x32_bf16 v[8:11], v[222:225], v[202:205], v[8:11]
	v_mfma_f32_16x16x32_bf16 v[4:7], v[230:233], v[202:205], v[4:7]
	s_add_u32 s3, s3, 0x100
	s_addc_u32 vcc_lo, vcc_lo, 0
	s_add_u32 vcc_hi, vcc_hi, 0x100
	s_addc_u32 s46, s46, 0
	s_cmp_lt_i32 s2, s57
	s_barrier
	s_cbranch_scc1 .LBB0_206
	s_movk_i32 s92, 0x90
	s_mov_b32 s93, 0x3f317217
